# v85 + residual-GEMM epilogues: row-sum exchanges via v_permlane16_swap/v_permlane32_swap instead of ds_bpermute
# speedup vs baseline: 1.0052x; 1.0052x over previous
.LBB0_1088:
	s_lshl_b32 s0, s5, 8
	v_mov_b32_e32 v32, v155
	v_mov_b32_e32 v130, v154
	s_add_i32 s0, s0, s93
	s_lshl_b32 s82, s4, 2
	v_add_u32_e32 v150, s0, v32
	s_lshl_b32 s0, s4, 9
	s_or_b32 s0, s0, s94
	v_lshlrev_b32_e32 v32, 11, v150
	v_lshlrev_b32_e32 v131, 4, v130
	v_add3_u32 v158, s0, v131, v32
	global_load_dwordx4 v[160:163], v158, s[52:53]
	v_add_u32_e32 v151, 0x100, v158
	global_load_dwordx4 v[164:167], v151, s[52:53]
	v_add_u32_e32 v32, 0x8000, v158
	v_add_u32_e32 v152, 0x8100, v158
	v_cmp_eq_u32_e32 vcc, 0, v130
	global_load_dwordx4 v[134:137], v32, s[52:53]
	global_load_dwordx4 v[130:133], v152, s[52:53]
	s_ashr_i32 s83, s82, 31
	s_waitcnt vmcnt(0)
	v_lshlrev_b32_e32 v168, 16, v160
	v_and_b32_e32 v169, 0xffff0000, v160
	v_lshlrev_b32_e32 v160, 16, v161
	v_and_b32_e32 v161, 0xffff0000, v161
	v_lshlrev_b32_e32 v170, 16, v162
	v_and_b32_e32 v171, 0xffff0000, v162
	v_lshlrev_b32_e32 v162, 16, v163
	v_and_b32_e32 v163, 0xffff0000, v163
	v_pk_add_f32 v[128:129], v[128:129], v[160:161]
	v_pk_add_f32 v[126:127], v[126:127], v[168:169]
	v_pk_add_f32 v[160:161], v[124:125], v[162:163]
	v_pk_add_f32 v[162:163], v[122:123], v[170:171]
	v_cvt_pk_bf16_f32 v122, v126, v127
	v_cvt_pk_bf16_f32 v123, v128, v129
	s_nop 0
	v_cvt_pk_bf16_f32 v124, v162, v163
	v_cvt_pk_bf16_f32 v125, v160, v161
	global_store_dwordx4 v158, v[122:125], s[52:53]
	s_nop 1
	v_mul_f32_e32 v122, v127, v127
	v_mul_f32_e32 v123, v129, v129
	v_fmac_f32_e32 v122, v126, v126
	v_fmac_f32_e32 v123, v128, v128
	v_add_f32_e32 v122, v122, v123
	v_mul_f32_e32 v123, v163, v163
	v_fmac_f32_e32 v123, v162, v162
	v_add_f32_e32 v122, v123, v122
	v_mul_f32_e32 v123, v161, v161
	v_fmac_f32_e32 v123, v160, v160
	v_add_f32_e32 v153, v123, v122
	v_lshlrev_b32_e32 v122, 16, v164
	v_and_b32_e32 v123, 0xffff0000, v164
	v_lshlrev_b32_e32 v124, 16, v165
	v_and_b32_e32 v125, 0xffff0000, v165
	v_lshlrev_b32_e32 v126, 16, v166
	v_and_b32_e32 v127, 0xffff0000, v166
	v_lshlrev_b32_e32 v128, 16, v167
	v_and_b32_e32 v129, 0xffff0000, v167
	v_pk_add_f32 v[120:121], v[120:121], v[124:125]
	v_pk_add_f32 v[118:119], v[118:119], v[122:123]
	v_pk_add_f32 v[124:125], v[114:115], v[126:127]
	v_cvt_pk_bf16_f32 v114, v118, v119
	v_cvt_pk_bf16_f32 v115, v120, v121
	v_pk_add_f32 v[122:123], v[116:117], v[128:129]
	v_cvt_pk_bf16_f32 v116, v124, v125
	s_nop 0
	v_cvt_pk_bf16_f32 v117, v122, v123
	global_store_dwordx4 v151, v[114:117], s[52:53]
	s_nop 1
	v_mul_f32_e32 v114, v119, v119
	v_mul_f32_e32 v115, v121, v121
	v_fmac_f32_e32 v114, v118, v118
	v_fmac_f32_e32 v115, v120, v120
	v_add_f32_e32 v114, v114, v115
	v_mul_f32_e32 v115, v125, v125
	v_fmac_f32_e32 v115, v124, v124
	v_add_f32_e32 v114, v115, v114
	v_mul_f32_e32 v115, v123, v123
	v_fmac_f32_e32 v115, v122, v122
	v_and_b32_e32 v116, 64, v238
	v_add_f32_e32 v114, v115, v114
	v_xor_b32_e32 v115, 16, v238
	v_add_u32_e32 v116, 64, v116
	v_cmp_lt_i32_e64 s[0:1], v115, v116
	v_add_f32_e32 v114, v153, v114
	s_nop 0
	v_cndmask_b32_e64 v115, v238, v115, s[0:1]
	v_lshlrev_b32_e32 v124, 2, v115
	v_mov_b32_e32 v115, v114
	s_nop 1
	v_permlane16_swap_b32 v115, v114
	s_waitcnt lgkmcnt(0)
	v_add_f32_e32 v114, v114, v115
	v_xor_b32_e32 v115, 32, v238
	v_cmp_lt_i32_e64 s[0:1], v115, v116
	s_nop 1
	v_cndmask_b32_e64 v115, v238, v115, s[0:1]
	v_lshlrev_b32_e32 v125, 2, v115
	v_mov_b32_e32 v115, v114
	s_nop 1
	v_permlane32_swap_b32 v115, v114
	s_and_saveexec_b64 s[0:1], vcc
	s_cbranch_execz .LBB0_1090
	v_ashrrev_i32_e32 v151, 31, v150
	s_waitcnt lgkmcnt(0)
	v_add_f32_e32 v116, v114, v115
	v_lshlrev_b64 v[114:115], 6, v[150:151]
	v_lshl_add_u64 v[114:115], s[54:55], 0, v[114:115]
	v_lshl_add_u64 v[114:115], s[82:83], 2, v[114:115]
	s_lshl_b32 s16, s88, 2
	v_lshl_add_u64 v[114:115], v[114:115], 0, s[16:17]
	global_store_dword v[114:115], v116, off
.LBB0_1090:
	s_or_b64 exec, exec, s[0:1]
	v_lshl_add_u64 v[126:127], s[52:53], 0, v[32:33]
	v_add_u32_e32 v32, 0x10000, v158
	v_add_u32_e32 v122, 0x10100, v158
	global_load_dwordx4 v[118:121], v32, s[52:53]
	s_waitcnt lgkmcnt(0)
	global_load_dwordx4 v[114:117], v122, s[52:53]
	v_mov_b32_e32 v153, v33
	v_lshl_add_u64 v[128:129], s[52:53], 0, v[152:153]
	v_lshlrev_b32_e32 v152, 16, v134
	v_and_b32_e32 v153, 0xffff0000, v134
	v_lshlrev_b32_e32 v134, 16, v135
	v_and_b32_e32 v135, 0xffff0000, v135
	v_lshlrev_b32_e32 v160, 16, v136
	v_and_b32_e32 v161, 0xffff0000, v136
	v_lshlrev_b32_e32 v136, 16, v137
	v_and_b32_e32 v137, 0xffff0000, v137
	v_pk_add_f32 v[110:111], v[110:111], v[152:153]
	v_pk_add_f32 v[112:113], v[112:113], v[134:135]
	v_pk_add_f32 v[134:135], v[108:109], v[136:137]
	v_pk_add_f32 v[108:109], v[106:107], v[160:161]
	v_cvt_pk_bf16_f32 v106, v110, v111
	v_mul_f32_e32 v111, v111, v111
	v_fmac_f32_e32 v111, v110, v110
	v_mul_f32_e32 v110, v113, v113
	v_fmac_f32_e32 v110, v112, v112
	v_add_f32_e32 v110, v111, v110
	v_mul_f32_e32 v111, v109, v109
	v_fmac_f32_e32 v111, v108, v108
	v_add_f32_e32 v110, v111, v110
	v_mul_f32_e32 v111, v135, v135
	v_fmac_f32_e32 v111, v134, v134
	v_cvt_pk_bf16_f32 v107, v112, v113
	v_add_f32_e32 v123, v111, v110
	v_lshlrev_b32_e32 v110, 16, v130
	v_and_b32_e32 v111, 0xffff0000, v130
	v_lshlrev_b32_e32 v112, 16, v131
	v_and_b32_e32 v113, 0xffff0000, v131
	v_lshlrev_b32_e32 v130, 16, v132
	v_and_b32_e32 v131, 0xffff0000, v132
	v_pk_add_f32 v[104:105], v[104:105], v[112:113]
	v_pk_add_f32 v[102:103], v[102:103], v[110:111]
	v_pk_add_f32 v[112:113], v[98:99], v[130:131]
	v_mul_f32_e32 v98, v103, v103
	v_mul_f32_e32 v99, v105, v105
	v_fmac_f32_e32 v98, v102, v102
	v_fmac_f32_e32 v99, v104, v104
	v_lshlrev_b32_e32 v132, 16, v133
	v_and_b32_e32 v133, 0xffff0000, v133
	v_add_f32_e32 v98, v98, v99
	v_mul_f32_e32 v99, v113, v113
	v_pk_add_f32 v[110:111], v[100:101], v[132:133]
	v_fmac_f32_e32 v99, v112, v112
	v_add_f32_e32 v98, v99, v98
	v_mul_f32_e32 v99, v111, v111
	v_fmac_f32_e32 v99, v110, v110
	v_add_f32_e32 v98, v99, v98
	v_add_f32_e32 v98, v123, v98
	v_mov_b32_e32 v99, v98
	s_nop 1
	v_permlane16_swap_b32 v99, v98
	v_cvt_pk_bf16_f32 v108, v108, v109
	v_cvt_pk_bf16_f32 v109, v134, v135
	global_store_dwordx4 v[126:127], v[106:109], off
	v_cvt_pk_bf16_f32 v100, v102, v103
	s_waitcnt lgkmcnt(0)
	v_add_f32_e32 v98, v98, v99
	v_mov_b32_e32 v99, v98
	s_nop 1
	v_permlane32_swap_b32 v99, v98
	v_cvt_pk_bf16_f32 v101, v104, v105
	v_cvt_pk_bf16_f32 v102, v112, v113
	v_cvt_pk_bf16_f32 v103, v110, v111
	global_store_dwordx4 v[128:129], v[100:103], off
	s_and_saveexec_b64 s[0:1], vcc
	s_cbranch_execz .LBB0_1092
	v_add_u32_e32 v100, 16, v150
	v_ashrrev_i32_e32 v101, 31, v100
	s_waitcnt lgkmcnt(0)
	v_add_f32_e32 v102, v98, v99
	v_lshlrev_b64 v[98:99], 6, v[100:101]
	v_lshl_add_u64 v[98:99], s[54:55], 0, v[98:99]
	v_lshl_add_u64 v[98:99], s[82:83], 2, v[98:99]
	s_lshl_b32 s16, s88, 2
	v_lshl_add_u64 v[98:99], v[98:99], 0, s[16:17]
	global_store_dword v[98:99], v102, off
.LBB0_1092:
	s_or_b64 exec, exec, s[0:1]
	v_lshl_add_u64 v[108:109], s[52:53], 0, v[32:33]
	v_add_u32_e32 v32, 0x18000, v158
	v_add_u32_e32 v106, 0x18100, v158
	global_load_dwordx4 v[102:105], v32, s[52:53]
	s_waitcnt lgkmcnt(0)
	global_load_dwordx4 v[98:101], v106, s[52:53]
	v_mov_b32_e32 v123, v33
	s_waitcnt vmcnt(5)
	v_lshlrev_b32_e32 v112, 16, v118
	v_and_b32_e32 v113, 0xffff0000, v118
	v_lshl_add_u64 v[110:111], s[52:53], 0, v[122:123]
	v_lshlrev_b32_e32 v118, 16, v119
	v_and_b32_e32 v119, 0xffff0000, v119
	v_lshlrev_b32_e32 v122, 16, v120
	v_and_b32_e32 v123, 0xffff0000, v120
	v_lshlrev_b32_e32 v120, 16, v121
	v_and_b32_e32 v121, 0xffff0000, v121
	v_pk_add_f32 v[94:95], v[94:95], v[112:113]
	v_pk_add_f32 v[96:97], v[96:97], v[118:119]
	v_pk_add_f32 v[112:113], v[92:93], v[120:121]
	v_pk_add_f32 v[92:93], v[90:91], v[122:123]
	v_cvt_pk_bf16_f32 v90, v94, v95
	v_mul_f32_e32 v95, v95, v95
	v_fmac_f32_e32 v95, v94, v94
	v_mul_f32_e32 v94, v97, v97
	v_fmac_f32_e32 v94, v96, v96
	v_add_f32_e32 v94, v95, v94
	v_mul_f32_e32 v95, v93, v93
	v_fmac_f32_e32 v95, v92, v92
	v_add_f32_e32 v94, v95, v94
	v_mul_f32_e32 v95, v113, v113
	v_fmac_f32_e32 v95, v112, v112
	v_cvt_pk_bf16_f32 v91, v96, v97
	v_add_f32_e32 v107, v95, v94
	s_waitcnt vmcnt(4)
	v_lshlrev_b32_e32 v94, 16, v114
	v_and_b32_e32 v95, 0xffff0000, v114
	v_lshlrev_b32_e32 v96, 16, v115
	v_and_b32_e32 v97, 0xffff0000, v115
	v_lshlrev_b32_e32 v114, 16, v116
	v_and_b32_e32 v115, 0xffff0000, v116
	v_pk_add_f32 v[88:89], v[88:89], v[96:97]
	v_pk_add_f32 v[86:87], v[86:87], v[94:95]
	v_pk_add_f32 v[96:97], v[82:83], v[114:115]
	v_mul_f32_e32 v82, v87, v87
	v_mul_f32_e32 v83, v89, v89
	v_fmac_f32_e32 v82, v86, v86
	v_fmac_f32_e32 v83, v88, v88
	v_lshlrev_b32_e32 v116, 16, v117
	v_and_b32_e32 v117, 0xffff0000, v117
	v_add_f32_e32 v82, v82, v83
	v_mul_f32_e32 v83, v97, v97
	v_pk_add_f32 v[94:95], v[84:85], v[116:117]
	v_fmac_f32_e32 v83, v96, v96
	v_add_f32_e32 v82, v83, v82
	v_mul_f32_e32 v83, v95, v95
	v_fmac_f32_e32 v83, v94, v94
	v_add_f32_e32 v82, v83, v82
	v_add_f32_e32 v82, v107, v82
	v_mov_b32_e32 v83, v82
	s_nop 1
	v_permlane16_swap_b32 v83, v82
	v_cvt_pk_bf16_f32 v92, v92, v93
	v_cvt_pk_bf16_f32 v93, v112, v113
	global_store_dwordx4 v[108:109], v[90:93], off
	v_cvt_pk_bf16_f32 v84, v86, v87
	s_waitcnt lgkmcnt(0)
	v_add_f32_e32 v82, v82, v83
	v_mov_b32_e32 v83, v82
	s_nop 1
	v_permlane32_swap_b32 v83, v82
	v_cvt_pk_bf16_f32 v85, v88, v89
	v_cvt_pk_bf16_f32 v86, v96, v97
	v_cvt_pk_bf16_f32 v87, v94, v95
	global_store_dwordx4 v[110:111], v[84:87], off
	s_and_saveexec_b64 s[0:1], vcc
	s_cbranch_execz .LBB0_1094
	v_add_u32_e32 v84, 32, v150
	v_ashrrev_i32_e32 v85, 31, v84
	s_waitcnt lgkmcnt(0)
	v_add_f32_e32 v86, v82, v83
	v_lshlrev_b64 v[82:83], 6, v[84:85]
	v_lshl_add_u64 v[82:83], s[54:55], 0, v[82:83]
	v_lshl_add_u64 v[82:83], s[82:83], 2, v[82:83]
	s_lshl_b32 s16, s88, 2
	v_lshl_add_u64 v[82:83], v[82:83], 0, s[16:17]
	global_store_dword v[82:83], v86, off
.LBB0_1094:
	s_or_b64 exec, exec, s[0:1]
	v_lshl_add_u64 v[92:93], s[52:53], 0, v[32:33]
	v_add_u32_e32 v32, 0x40000, v158
	v_add_u32_e32 v90, 0x40100, v158
	global_load_dwordx4 v[86:89], v32, s[52:53]
	s_waitcnt lgkmcnt(0)
	global_load_dwordx4 v[82:85], v90, s[52:53]
	v_mov_b32_e32 v107, v33
	s_waitcnt vmcnt(5)
	v_lshlrev_b32_e32 v96, 16, v102
	v_and_b32_e32 v97, 0xffff0000, v102
	v_lshl_add_u64 v[94:95], s[52:53], 0, v[106:107]
	v_lshlrev_b32_e32 v102, 16, v103
	v_and_b32_e32 v103, 0xffff0000, v103
	v_lshlrev_b32_e32 v106, 16, v104
	v_and_b32_e32 v107, 0xffff0000, v104
	v_lshlrev_b32_e32 v104, 16, v105
	v_and_b32_e32 v105, 0xffff0000, v105
	v_pk_add_f32 v[78:79], v[78:79], v[96:97]
	v_pk_add_f32 v[80:81], v[80:81], v[102:103]
	v_pk_add_f32 v[96:97], v[76:77], v[104:105]
	v_pk_add_f32 v[76:77], v[74:75], v[106:107]
	v_cvt_pk_bf16_f32 v74, v78, v79
	v_mul_f32_e32 v79, v79, v79
	v_fmac_f32_e32 v79, v78, v78
	v_mul_f32_e32 v78, v81, v81
	v_fmac_f32_e32 v78, v80, v80
	v_add_f32_e32 v78, v79, v78
	v_mul_f32_e32 v79, v77, v77
	v_fmac_f32_e32 v79, v76, v76
	v_add_f32_e32 v78, v79, v78
	v_mul_f32_e32 v79, v97, v97
	v_fmac_f32_e32 v79, v96, v96
	v_cvt_pk_bf16_f32 v75, v80, v81
	v_add_f32_e32 v91, v79, v78
	s_waitcnt vmcnt(4)
	v_lshlrev_b32_e32 v78, 16, v98
	v_and_b32_e32 v79, 0xffff0000, v98
	v_lshlrev_b32_e32 v80, 16, v99
	v_and_b32_e32 v81, 0xffff0000, v99
	v_lshlrev_b32_e32 v98, 16, v100
	v_and_b32_e32 v99, 0xffff0000, v100
	v_pk_add_f32 v[72:73], v[72:73], v[80:81]
	v_pk_add_f32 v[70:71], v[70:71], v[78:79]
	v_pk_add_f32 v[80:81], v[66:67], v[98:99]
	v_mul_f32_e32 v66, v71, v71
	v_mul_f32_e32 v67, v73, v73
	v_fmac_f32_e32 v66, v70, v70
	v_fmac_f32_e32 v67, v72, v72
	v_lshlrev_b32_e32 v100, 16, v101
	v_and_b32_e32 v101, 0xffff0000, v101
	v_add_f32_e32 v66, v66, v67
	v_mul_f32_e32 v67, v81, v81
	v_pk_add_f32 v[78:79], v[68:69], v[100:101]
	v_fmac_f32_e32 v67, v80, v80
	v_add_f32_e32 v66, v67, v66
	v_mul_f32_e32 v67, v79, v79
	v_fmac_f32_e32 v67, v78, v78
	v_add_f32_e32 v66, v67, v66
	v_add_f32_e32 v66, v91, v66
	v_mov_b32_e32 v67, v66
	s_nop 1
	v_permlane16_swap_b32 v67, v66
	v_cvt_pk_bf16_f32 v76, v76, v77
	v_cvt_pk_bf16_f32 v77, v96, v97
	global_store_dwordx4 v[92:93], v[74:77], off
	v_cvt_pk_bf16_f32 v68, v70, v71
	s_waitcnt lgkmcnt(0)
	v_add_f32_e32 v66, v66, v67
	v_mov_b32_e32 v67, v66
	s_nop 1
	v_permlane32_swap_b32 v67, v66
	v_cvt_pk_bf16_f32 v69, v72, v73
	v_cvt_pk_bf16_f32 v70, v80, v81
	v_cvt_pk_bf16_f32 v71, v78, v79
	global_store_dwordx4 v[94:95], v[68:71], off
	s_and_saveexec_b64 s[0:1], vcc
	s_cbranch_execz .LBB0_1096
	v_add_u32_e32 v68, 48, v150
	v_ashrrev_i32_e32 v69, 31, v68
	s_waitcnt lgkmcnt(0)
	v_add_f32_e32 v70, v66, v67
	v_lshlrev_b64 v[66:67], 6, v[68:69]
	v_lshl_add_u64 v[66:67], s[54:55], 0, v[66:67]
	v_lshl_add_u64 v[66:67], s[82:83], 2, v[66:67]
	s_lshl_b32 s16, s88, 2
	v_lshl_add_u64 v[66:67], v[66:67], 0, s[16:17]
	global_store_dword v[66:67], v70, off
.LBB0_1096:
	s_or_b64 exec, exec, s[0:1]
	v_lshl_add_u64 v[76:77], s[52:53], 0, v[32:33]
	v_add_u32_e32 v32, 0x48000, v158
	v_add_u32_e32 v74, 0x48100, v158
	global_load_dwordx4 v[70:73], v32, s[52:53]
	s_waitcnt lgkmcnt(0)
	global_load_dwordx4 v[66:69], v74, s[52:53]
	v_mov_b32_e32 v91, v33
	s_waitcnt vmcnt(5)
	v_lshlrev_b32_e32 v80, 16, v86
	v_and_b32_e32 v81, 0xffff0000, v86
	v_lshl_add_u64 v[78:79], s[52:53], 0, v[90:91]
	v_lshlrev_b32_e32 v86, 16, v87
	v_and_b32_e32 v87, 0xffff0000, v87
	v_lshlrev_b32_e32 v90, 16, v88
	v_and_b32_e32 v91, 0xffff0000, v88
	v_lshlrev_b32_e32 v88, 16, v89
	v_and_b32_e32 v89, 0xffff0000, v89
	v_pk_add_f32 v[62:63], v[62:63], v[80:81]
	v_pk_add_f32 v[64:65], v[64:65], v[86:87]
	v_pk_add_f32 v[80:81], v[60:61], v[88:89]
	v_pk_add_f32 v[60:61], v[58:59], v[90:91]
	v_cvt_pk_bf16_f32 v58, v62, v63
	v_mul_f32_e32 v63, v63, v63
	v_fmac_f32_e32 v63, v62, v62
	v_mul_f32_e32 v62, v65, v65
	v_fmac_f32_e32 v62, v64, v64
	v_add_f32_e32 v62, v63, v62
	v_mul_f32_e32 v63, v61, v61
	v_fmac_f32_e32 v63, v60, v60
	v_add_f32_e32 v62, v63, v62
	v_mul_f32_e32 v63, v81, v81
	v_fmac_f32_e32 v63, v80, v80
	v_cvt_pk_bf16_f32 v59, v64, v65
	v_add_f32_e32 v75, v63, v62
	s_waitcnt vmcnt(4)
	v_lshlrev_b32_e32 v62, 16, v82
	v_and_b32_e32 v63, 0xffff0000, v82
	v_lshlrev_b32_e32 v64, 16, v83
	v_and_b32_e32 v65, 0xffff0000, v83
	v_lshlrev_b32_e32 v82, 16, v84
	v_and_b32_e32 v83, 0xffff0000, v84
	v_pk_add_f32 v[56:57], v[56:57], v[64:65]
	v_pk_add_f32 v[54:55], v[54:55], v[62:63]
	v_pk_add_f32 v[64:65], v[50:51], v[82:83]
	v_mul_f32_e32 v50, v55, v55
	v_mul_f32_e32 v51, v57, v57
	v_fmac_f32_e32 v50, v54, v54
	v_fmac_f32_e32 v51, v56, v56
	v_lshlrev_b32_e32 v84, 16, v85
	v_and_b32_e32 v85, 0xffff0000, v85
	v_add_f32_e32 v50, v50, v51
	v_mul_f32_e32 v51, v65, v65
	v_pk_add_f32 v[62:63], v[52:53], v[84:85]
	v_fmac_f32_e32 v51, v64, v64
	v_add_f32_e32 v50, v51, v50
	v_mul_f32_e32 v51, v63, v63
	v_fmac_f32_e32 v51, v62, v62
	v_add_f32_e32 v50, v51, v50
	v_add_f32_e32 v50, v75, v50
	v_mov_b32_e32 v51, v50
	s_nop 1
	v_permlane16_swap_b32 v51, v50
	v_cvt_pk_bf16_f32 v60, v60, v61
	v_cvt_pk_bf16_f32 v61, v80, v81
	global_store_dwordx4 v[76:77], v[58:61], off
	v_cvt_pk_bf16_f32 v52, v54, v55
	s_waitcnt lgkmcnt(0)
	v_add_f32_e32 v50, v50, v51
	v_mov_b32_e32 v51, v50
	s_nop 1
	v_permlane32_swap_b32 v51, v50
	v_cvt_pk_bf16_f32 v53, v56, v57
	v_cvt_pk_bf16_f32 v54, v64, v65
	v_cvt_pk_bf16_f32 v55, v62, v63
	global_store_dwordx4 v[78:79], v[52:55], off
	s_and_saveexec_b64 s[0:1], vcc
	s_cbranch_execz .LBB0_1098
	v_add_u32_e32 v52, 0x80, v150
	v_ashrrev_i32_e32 v53, 31, v52
	s_waitcnt lgkmcnt(0)
	v_add_f32_e32 v54, v50, v51
	v_lshlrev_b64 v[50:51], 6, v[52:53]
	v_lshl_add_u64 v[50:51], s[54:55], 0, v[50:51]
	v_lshl_add_u64 v[50:51], s[82:83], 2, v[50:51]
	s_lshl_b32 s16, s88, 2
	v_lshl_add_u64 v[50:51], v[50:51], 0, s[16:17]
	global_store_dword v[50:51], v54, off
.LBB0_1098:
	s_or_b64 exec, exec, s[0:1]
	v_lshl_add_u64 v[60:61], s[52:53], 0, v[32:33]
	v_add_u32_e32 v32, 0x50000, v158
	v_add_u32_e32 v58, 0x50100, v158
	global_load_dwordx4 v[54:57], v32, s[52:53]
	s_waitcnt lgkmcnt(0)
	global_load_dwordx4 v[50:53], v58, s[52:53]
	v_mov_b32_e32 v75, v33
	s_waitcnt vmcnt(5)
	v_lshlrev_b32_e32 v64, 16, v70
	v_and_b32_e32 v65, 0xffff0000, v70
	v_lshl_add_u64 v[62:63], s[52:53], 0, v[74:75]
	v_lshlrev_b32_e32 v70, 16, v71
	v_and_b32_e32 v71, 0xffff0000, v71
	v_lshlrev_b32_e32 v74, 16, v72
	v_and_b32_e32 v75, 0xffff0000, v72
	v_lshlrev_b32_e32 v72, 16, v73
	v_and_b32_e32 v73, 0xffff0000, v73
	v_pk_add_f32 v[46:47], v[46:47], v[64:65]
	v_pk_add_f32 v[48:49], v[48:49], v[70:71]
	v_pk_add_f32 v[64:65], v[44:45], v[72:73]
	v_pk_add_f32 v[44:45], v[42:43], v[74:75]
	v_cvt_pk_bf16_f32 v42, v46, v47
	v_mul_f32_e32 v47, v47, v47
	v_fmac_f32_e32 v47, v46, v46
	v_mul_f32_e32 v46, v49, v49
	v_fmac_f32_e32 v46, v48, v48
	v_add_f32_e32 v46, v47, v46
	v_mul_f32_e32 v47, v45, v45
	v_fmac_f32_e32 v47, v44, v44
	v_add_f32_e32 v46, v47, v46
	v_mul_f32_e32 v47, v65, v65
	v_fmac_f32_e32 v47, v64, v64
	v_cvt_pk_bf16_f32 v43, v48, v49
	v_add_f32_e32 v59, v47, v46
	s_waitcnt vmcnt(4)
	v_lshlrev_b32_e32 v46, 16, v66
	v_and_b32_e32 v47, 0xffff0000, v66
	v_lshlrev_b32_e32 v48, 16, v67
	v_and_b32_e32 v49, 0xffff0000, v67
	v_lshlrev_b32_e32 v66, 16, v68
	v_and_b32_e32 v67, 0xffff0000, v68
	v_pk_add_f32 v[40:41], v[40:41], v[48:49]
	v_pk_add_f32 v[38:39], v[38:39], v[46:47]
	v_pk_add_f32 v[48:49], v[34:35], v[66:67]
	v_mul_f32_e32 v34, v39, v39
	v_mul_f32_e32 v35, v41, v41
	v_fmac_f32_e32 v34, v38, v38
	v_fmac_f32_e32 v35, v40, v40
	v_lshlrev_b32_e32 v68, 16, v69
	v_and_b32_e32 v69, 0xffff0000, v69
	v_add_f32_e32 v34, v34, v35
	v_mul_f32_e32 v35, v49, v49
	v_pk_add_f32 v[46:47], v[36:37], v[68:69]
	v_fmac_f32_e32 v35, v48, v48
	v_add_f32_e32 v34, v35, v34
	v_mul_f32_e32 v35, v47, v47
	v_fmac_f32_e32 v35, v46, v46
	v_add_f32_e32 v34, v35, v34
	v_add_f32_e32 v34, v59, v34
	v_mov_b32_e32 v35, v34
	s_nop 1
	v_permlane16_swap_b32 v35, v34
	v_cvt_pk_bf16_f32 v44, v44, v45
	v_cvt_pk_bf16_f32 v45, v64, v65
	global_store_dwordx4 v[60:61], v[42:45], off
	v_cvt_pk_bf16_f32 v36, v38, v39
	s_waitcnt lgkmcnt(0)
	v_add_f32_e32 v34, v34, v35
	v_mov_b32_e32 v35, v34
	s_nop 1
	v_permlane32_swap_b32 v35, v34
	v_cvt_pk_bf16_f32 v37, v40, v41
	v_cvt_pk_bf16_f32 v38, v48, v49
	v_cvt_pk_bf16_f32 v39, v46, v47
	global_store_dwordx4 v[62:63], v[36:39], off
	s_and_saveexec_b64 s[0:1], vcc
	s_cbranch_execz .LBB0_1100
	v_add_u32_e32 v36, 0x90, v150
	v_ashrrev_i32_e32 v37, 31, v36
	s_waitcnt lgkmcnt(0)
	v_add_f32_e32 v38, v34, v35
	v_lshlrev_b64 v[34:35], 6, v[36:37]
	v_lshl_add_u64 v[34:35], s[54:55], 0, v[34:35]
	v_lshl_add_u64 v[34:35], s[82:83], 2, v[34:35]
	s_lshl_b32 s16, s88, 2
	v_lshl_add_u64 v[34:35], v[34:35], 0, s[16:17]
	global_store_dword v[34:35], v38, off
.LBB0_1100:
	s_or_b64 exec, exec, s[0:1]
	v_lshl_add_u64 v[44:45], s[52:53], 0, v[32:33]
	v_add_u32_e32 v32, 0x58000, v158
	v_add_u32_e32 v42, 0x58100, v158
	global_load_dwordx4 v[38:41], v32, s[52:53]
	s_waitcnt lgkmcnt(0)
	global_load_dwordx4 v[34:37], v42, s[52:53]
	v_mov_b32_e32 v59, v33
	s_waitcnt vmcnt(5)
	v_lshlrev_b32_e32 v48, 16, v54
	v_and_b32_e32 v49, 0xffff0000, v54
	v_lshl_add_u64 v[46:47], s[52:53], 0, v[58:59]
	v_lshlrev_b32_e32 v54, 16, v55
	v_and_b32_e32 v55, 0xffff0000, v55
	v_lshlrev_b32_e32 v58, 16, v56
	v_and_b32_e32 v59, 0xffff0000, v56
	v_lshlrev_b32_e32 v56, 16, v57
	v_and_b32_e32 v57, 0xffff0000, v57
	v_pk_add_f32 v[28:29], v[28:29], v[48:49]
	v_pk_add_f32 v[30:31], v[30:31], v[54:55]
	v_pk_add_f32 v[48:49], v[26:27], v[56:57]
	v_pk_add_f32 v[26:27], v[24:25], v[58:59]
	v_cvt_pk_bf16_f32 v24, v28, v29
	v_mul_f32_e32 v29, v29, v29
	v_fmac_f32_e32 v29, v28, v28
	v_mul_f32_e32 v28, v31, v31
	v_fmac_f32_e32 v28, v30, v30
	v_add_f32_e32 v28, v29, v28
	v_mul_f32_e32 v29, v27, v27
	v_fmac_f32_e32 v29, v26, v26
	v_add_f32_e32 v28, v29, v28
	v_mul_f32_e32 v29, v49, v49
	v_fmac_f32_e32 v29, v48, v48
	v_cvt_pk_bf16_f32 v25, v30, v31
	v_add_f32_e32 v43, v29, v28
	s_waitcnt vmcnt(4)
	v_lshlrev_b32_e32 v28, 16, v50
	v_and_b32_e32 v29, 0xffff0000, v50
	v_lshlrev_b32_e32 v30, 16, v51
	v_and_b32_e32 v31, 0xffff0000, v51
	v_lshlrev_b32_e32 v50, 16, v52
	v_and_b32_e32 v51, 0xffff0000, v52
	v_pk_add_f32 v[22:23], v[22:23], v[30:31]
	v_pk_add_f32 v[20:21], v[20:21], v[28:29]
	v_pk_add_f32 v[30:31], v[16:17], v[50:51]
	v_mul_f32_e32 v16, v21, v21
	v_mul_f32_e32 v17, v23, v23
	v_fmac_f32_e32 v16, v20, v20
	v_fmac_f32_e32 v17, v22, v22
	v_lshlrev_b32_e32 v52, 16, v53
	v_and_b32_e32 v53, 0xffff0000, v53
	v_add_f32_e32 v16, v16, v17
	v_mul_f32_e32 v17, v31, v31
	v_pk_add_f32 v[28:29], v[18:19], v[52:53]
	v_fmac_f32_e32 v17, v30, v30
	v_add_f32_e32 v16, v17, v16
	v_mul_f32_e32 v17, v29, v29
	v_fmac_f32_e32 v17, v28, v28
	v_add_f32_e32 v16, v17, v16
	v_add_f32_e32 v16, v43, v16
	v_mov_b32_e32 v17, v16
	s_nop 1
	v_permlane16_swap_b32 v17, v16
	v_cvt_pk_bf16_f32 v26, v26, v27
	v_cvt_pk_bf16_f32 v27, v48, v49
	global_store_dwordx4 v[44:45], v[24:27], off
	v_cvt_pk_bf16_f32 v18, v20, v21
	s_waitcnt lgkmcnt(0)
	v_add_f32_e32 v16, v16, v17
	v_mov_b32_e32 v17, v16
	s_nop 1
	v_permlane32_swap_b32 v17, v16
	v_cvt_pk_bf16_f32 v19, v22, v23
	v_cvt_pk_bf16_f32 v20, v30, v31
	v_cvt_pk_bf16_f32 v21, v28, v29
	global_store_dwordx4 v[46:47], v[18:21], off
	s_and_saveexec_b64 s[0:1], vcc
	s_cbranch_execz .LBB0_1102
	v_add_u32_e32 v18, 0xa0, v150
	v_ashrrev_i32_e32 v19, 31, v18
	s_waitcnt lgkmcnt(0)
	v_add_f32_e32 v20, v16, v17
	v_lshlrev_b64 v[16:17], 6, v[18:19]
	v_lshl_add_u64 v[16:17], s[54:55], 0, v[16:17]
	v_lshl_add_u64 v[16:17], s[82:83], 2, v[16:17]
	s_lshl_b32 s16, s88, 2
	v_lshl_add_u64 v[16:17], v[16:17], 0, s[16:17]
	global_store_dword v[16:17], v20, off
.LBB0_1102:
	s_or_b64 exec, exec, s[0:1]
	s_waitcnt vmcnt(3)
	v_lshlrev_b32_e32 v20, 16, v38
	v_and_b32_e32 v21, 0xffff0000, v38
	v_lshlrev_b32_e32 v22, 16, v39
	v_and_b32_e32 v23, 0xffff0000, v39
	v_lshlrev_b32_e32 v24, 16, v40
	v_and_b32_e32 v25, 0xffff0000, v40
	v_lshlrev_b32_e32 v26, 16, v41
	v_and_b32_e32 v27, 0xffff0000, v41
	v_pk_add_f32 v[12:13], v[12:13], v[20:21]
	v_pk_add_f32 v[14:15], v[14:15], v[22:23]
	v_pk_add_f32 v[20:21], v[10:11], v[26:27]
	v_pk_add_f32 v[10:11], v[8:9], v[24:25]
	v_cvt_pk_bf16_f32 v8, v12, v13
	v_mul_f32_e32 v13, v13, v13
	v_fmac_f32_e32 v13, v12, v12
	v_mul_f32_e32 v12, v15, v15
	v_fmac_f32_e32 v12, v14, v14
	v_add_f32_e32 v12, v13, v12
	v_mul_f32_e32 v13, v11, v11
	v_fmac_f32_e32 v13, v10, v10
	v_add_f32_e32 v12, v13, v12
	v_mul_f32_e32 v13, v21, v21
	v_fmac_f32_e32 v13, v20, v20
	v_cvt_pk_bf16_f32 v9, v14, v15
	v_add_f32_e32 v26, v13, v12
	s_waitcnt vmcnt(2)
	v_lshlrev_b32_e32 v12, 16, v34
	v_and_b32_e32 v13, 0xffff0000, v34
	v_lshlrev_b32_e32 v14, 16, v35
	v_and_b32_e32 v15, 0xffff0000, v35
	v_lshlrev_b32_e32 v22, 16, v36
	v_and_b32_e32 v23, 0xffff0000, v36
	v_pk_add_f32 v[6:7], v[6:7], v[14:15]
	v_pk_add_f32 v[4:5], v[4:5], v[12:13]
	v_pk_add_f32 v[14:15], v[0:1], v[22:23]
	v_mul_f32_e32 v0, v5, v5
	v_mul_f32_e32 v1, v7, v7
	v_fmac_f32_e32 v0, v4, v4
	v_fmac_f32_e32 v1, v6, v6
	v_lshlrev_b32_e32 v24, 16, v37
	v_and_b32_e32 v25, 0xffff0000, v37
	v_add_f32_e32 v0, v0, v1
	v_mul_f32_e32 v1, v15, v15
	v_pk_add_f32 v[12:13], v[2:3], v[24:25]
	v_fmac_f32_e32 v1, v14, v14
	v_add_f32_e32 v0, v1, v0
	v_mul_f32_e32 v1, v13, v13
	v_fmac_f32_e32 v1, v12, v12
	v_add_f32_e32 v0, v1, v0
	v_add_f32_e32 v0, v26, v0
	v_mov_b32_e32 v1, v0
	s_nop 1
	v_permlane16_swap_b32 v1, v0
	v_mov_b32_e32 v43, v33
	s_waitcnt lgkmcnt(1)
	v_lshl_add_u64 v[16:17], s[52:53], 0, v[32:33]
	v_lshl_add_u64 v[18:19], s[52:53], 0, v[42:43]
	v_cvt_pk_bf16_f32 v10, v10, v11
	s_waitcnt lgkmcnt(0)
	v_add_f32_e32 v0, v0, v1
	v_mov_b32_e32 v1, v0
	s_nop 1
	v_permlane32_swap_b32 v1, v0
	v_cvt_pk_bf16_f32 v11, v20, v21
	global_store_dwordx4 v[16:17], v[8:11], off
	v_cvt_pk_bf16_f32 v2, v4, v5
	v_cvt_pk_bf16_f32 v3, v6, v7
	v_cvt_pk_bf16_f32 v4, v14, v15
	v_cvt_pk_bf16_f32 v5, v12, v13
	global_store_dwordx4 v[18:19], v[2:5], off
	s_and_saveexec_b64 s[0:1], vcc
	s_cbranch_execz .LBB0_1104
	v_add_u32_e32 v2, 0xb0, v150
	v_ashrrev_i32_e32 v3, 31, v2
	s_waitcnt lgkmcnt(0)
	v_add_f32_e32 v4, v0, v1
	v_lshlrev_b64 v[0:1], 6, v[2:3]
	v_lshl_add_u64 v[0:1], s[54:55], 0, v[0:1]
	v_lshl_add_u64 v[0:1], s[82:83], 2, v[0:1]
	s_lshl_b32 s16, s88, 2
	v_lshl_add_u64 v[0:1], v[0:1], 0, s[16:17]
	global_store_dword v[0:1], v4, off

.LBB0_1272:
	s_lshl_b32 s0, s5, 8
	v_mov_b32_e32 v32, v155
	v_mov_b32_e32 v130, v154
	s_add_i32 s0, s0, s87
	s_lshl_b32 s70, s4, 2
	v_add_u32_e32 v150, s0, v32
	s_lshl_b32 s0, s4, 9
	s_or_b32 s0, s0, s88
	v_lshlrev_b32_e32 v32, 11, v150
	v_lshlrev_b32_e32 v131, 4, v130
	v_add3_u32 v158, s0, v131, v32
	global_load_dwordx4 v[160:163], v158, s[42:43]
	v_add_u32_e32 v151, 0x100, v158
	global_load_dwordx4 v[164:167], v151, s[42:43]
	v_add_u32_e32 v32, 0x8000, v158
	v_add_u32_e32 v152, 0x8100, v158
	v_cmp_eq_u32_e32 vcc, 0, v130
	global_load_dwordx4 v[134:137], v32, s[42:43]
	global_load_dwordx4 v[130:133], v152, s[42:43]
	s_ashr_i32 s71, s70, 31
	s_waitcnt vmcnt(0)
	v_lshlrev_b32_e32 v168, 16, v160
	v_and_b32_e32 v169, 0xffff0000, v160
	v_lshlrev_b32_e32 v160, 16, v161
	v_and_b32_e32 v161, 0xffff0000, v161
	v_lshlrev_b32_e32 v170, 16, v162
	v_and_b32_e32 v171, 0xffff0000, v162
	v_lshlrev_b32_e32 v162, 16, v163
	v_and_b32_e32 v163, 0xffff0000, v163
	v_pk_add_f32 v[128:129], v[128:129], v[160:161]
	v_pk_add_f32 v[126:127], v[126:127], v[168:169]
	v_pk_add_f32 v[160:161], v[124:125], v[162:163]
	v_pk_add_f32 v[162:163], v[122:123], v[170:171]
	v_cvt_pk_bf16_f32 v122, v126, v127
	v_cvt_pk_bf16_f32 v123, v128, v129
	s_nop 0
	v_cvt_pk_bf16_f32 v124, v162, v163
	v_cvt_pk_bf16_f32 v125, v160, v161
	global_store_dwordx4 v158, v[122:125], s[42:43]
	s_nop 1
	v_mul_f32_e32 v122, v127, v127
	v_mul_f32_e32 v123, v129, v129
	v_fmac_f32_e32 v122, v126, v126
	v_fmac_f32_e32 v123, v128, v128
	v_add_f32_e32 v122, v122, v123
	v_mul_f32_e32 v123, v163, v163
	v_fmac_f32_e32 v123, v162, v162
	v_add_f32_e32 v122, v123, v122
	v_mul_f32_e32 v123, v161, v161
	v_fmac_f32_e32 v123, v160, v160
	v_add_f32_e32 v153, v123, v122
	v_lshlrev_b32_e32 v122, 16, v164
	v_and_b32_e32 v123, 0xffff0000, v164
	v_lshlrev_b32_e32 v124, 16, v165
	v_and_b32_e32 v125, 0xffff0000, v165
	v_lshlrev_b32_e32 v126, 16, v166
	v_and_b32_e32 v127, 0xffff0000, v166
	v_lshlrev_b32_e32 v128, 16, v167
	v_and_b32_e32 v129, 0xffff0000, v167
	v_pk_add_f32 v[120:121], v[120:121], v[124:125]
	v_pk_add_f32 v[118:119], v[118:119], v[122:123]
	v_pk_add_f32 v[124:125], v[114:115], v[126:127]
	v_cvt_pk_bf16_f32 v114, v118, v119
	v_cvt_pk_bf16_f32 v115, v120, v121
	v_pk_add_f32 v[122:123], v[116:117], v[128:129]
	v_cvt_pk_bf16_f32 v116, v124, v125
	s_nop 0
	v_cvt_pk_bf16_f32 v117, v122, v123
	global_store_dwordx4 v151, v[114:117], s[42:43]
	s_nop 1
	v_mul_f32_e32 v114, v119, v119
	v_mul_f32_e32 v115, v121, v121
	v_fmac_f32_e32 v114, v118, v118
	v_fmac_f32_e32 v115, v120, v120
	v_add_f32_e32 v114, v114, v115
	v_mul_f32_e32 v115, v125, v125
	v_fmac_f32_e32 v115, v124, v124
	v_add_f32_e32 v114, v115, v114
	v_mul_f32_e32 v115, v123, v123
	v_fmac_f32_e32 v115, v122, v122
	v_and_b32_e32 v116, 64, v238
	v_add_f32_e32 v114, v115, v114
	v_xor_b32_e32 v115, 16, v238
	v_add_u32_e32 v116, 64, v116
	v_cmp_lt_i32_e64 s[0:1], v115, v116
	v_add_f32_e32 v114, v153, v114
	s_nop 0
	v_cndmask_b32_e64 v115, v238, v115, s[0:1]
	v_lshlrev_b32_e32 v124, 2, v115
	v_mov_b32_e32 v115, v114
	s_nop 1
	v_permlane16_swap_b32 v115, v114
	s_waitcnt lgkmcnt(0)
	v_add_f32_e32 v114, v114, v115
	v_xor_b32_e32 v115, 32, v238
	v_cmp_lt_i32_e64 s[0:1], v115, v116
	s_nop 1
	v_cndmask_b32_e64 v115, v238, v115, s[0:1]
	v_lshlrev_b32_e32 v125, 2, v115
	v_mov_b32_e32 v115, v114
	s_nop 1
	v_permlane32_swap_b32 v115, v114
	s_and_saveexec_b64 s[0:1], vcc
	s_cbranch_execz .LBB0_1274
	v_ashrrev_i32_e32 v151, 31, v150
	s_waitcnt lgkmcnt(0)
	v_add_f32_e32 v116, v114, v115
	v_lshlrev_b64 v[114:115], 6, v[150:151]
	v_lshl_add_u64 v[114:115], s[44:45], 0, v[114:115]
	v_lshl_add_u64 v[114:115], s[70:71], 2, v[114:115]
	s_lshl_b32 s16, s86, 2
	v_lshl_add_u64 v[114:115], v[114:115], 0, s[16:17]
	global_store_dword v[114:115], v116, off
.LBB0_1274:
	s_or_b64 exec, exec, s[0:1]
	v_lshl_add_u64 v[126:127], s[42:43], 0, v[32:33]
	v_add_u32_e32 v32, 0x10000, v158
	v_add_u32_e32 v122, 0x10100, v158
	global_load_dwordx4 v[118:121], v32, s[42:43]
	s_waitcnt lgkmcnt(0)
	global_load_dwordx4 v[114:117], v122, s[42:43]
	v_mov_b32_e32 v153, v33
	v_lshl_add_u64 v[128:129], s[42:43], 0, v[152:153]
	v_lshlrev_b32_e32 v152, 16, v134
	v_and_b32_e32 v153, 0xffff0000, v134
	v_lshlrev_b32_e32 v134, 16, v135
	v_and_b32_e32 v135, 0xffff0000, v135
	v_lshlrev_b32_e32 v160, 16, v136
	v_and_b32_e32 v161, 0xffff0000, v136
	v_lshlrev_b32_e32 v136, 16, v137
	v_and_b32_e32 v137, 0xffff0000, v137
	v_pk_add_f32 v[110:111], v[110:111], v[152:153]
	v_pk_add_f32 v[112:113], v[112:113], v[134:135]
	v_pk_add_f32 v[134:135], v[108:109], v[136:137]
	v_pk_add_f32 v[108:109], v[106:107], v[160:161]
	v_cvt_pk_bf16_f32 v106, v110, v111
	v_mul_f32_e32 v111, v111, v111
	v_fmac_f32_e32 v111, v110, v110
	v_mul_f32_e32 v110, v113, v113
	v_fmac_f32_e32 v110, v112, v112
	v_add_f32_e32 v110, v111, v110
	v_mul_f32_e32 v111, v109, v109
	v_fmac_f32_e32 v111, v108, v108
	v_add_f32_e32 v110, v111, v110
	v_mul_f32_e32 v111, v135, v135
	v_fmac_f32_e32 v111, v134, v134
	v_cvt_pk_bf16_f32 v107, v112, v113
	v_add_f32_e32 v123, v111, v110
	v_lshlrev_b32_e32 v110, 16, v130
	v_and_b32_e32 v111, 0xffff0000, v130
	v_lshlrev_b32_e32 v112, 16, v131
	v_and_b32_e32 v113, 0xffff0000, v131
	v_lshlrev_b32_e32 v130, 16, v132
	v_and_b32_e32 v131, 0xffff0000, v132
	v_pk_add_f32 v[104:105], v[104:105], v[112:113]
	v_pk_add_f32 v[102:103], v[102:103], v[110:111]
	v_pk_add_f32 v[112:113], v[98:99], v[130:131]
	v_mul_f32_e32 v98, v103, v103
	v_mul_f32_e32 v99, v105, v105
	v_fmac_f32_e32 v98, v102, v102
	v_fmac_f32_e32 v99, v104, v104
	v_lshlrev_b32_e32 v132, 16, v133
	v_and_b32_e32 v133, 0xffff0000, v133
	v_add_f32_e32 v98, v98, v99
	v_mul_f32_e32 v99, v113, v113
	v_pk_add_f32 v[110:111], v[100:101], v[132:133]
	v_fmac_f32_e32 v99, v112, v112
	v_add_f32_e32 v98, v99, v98
	v_mul_f32_e32 v99, v111, v111
	v_fmac_f32_e32 v99, v110, v110
	v_add_f32_e32 v98, v99, v98
	v_add_f32_e32 v98, v123, v98
	v_mov_b32_e32 v99, v98
	s_nop 1
	v_permlane16_swap_b32 v99, v98
	v_cvt_pk_bf16_f32 v108, v108, v109
	v_cvt_pk_bf16_f32 v109, v134, v135
	global_store_dwordx4 v[126:127], v[106:109], off
	v_cvt_pk_bf16_f32 v100, v102, v103
	s_waitcnt lgkmcnt(0)
	v_add_f32_e32 v98, v98, v99
	v_mov_b32_e32 v99, v98
	s_nop 1
	v_permlane32_swap_b32 v99, v98
	v_cvt_pk_bf16_f32 v101, v104, v105
	v_cvt_pk_bf16_f32 v102, v112, v113
	v_cvt_pk_bf16_f32 v103, v110, v111
	global_store_dwordx4 v[128:129], v[100:103], off
	s_and_saveexec_b64 s[0:1], vcc
	s_cbranch_execz .LBB0_1276
	v_add_u32_e32 v100, 16, v150
	v_ashrrev_i32_e32 v101, 31, v100
	s_waitcnt lgkmcnt(0)
	v_add_f32_e32 v102, v98, v99
	v_lshlrev_b64 v[98:99], 6, v[100:101]
	v_lshl_add_u64 v[98:99], s[44:45], 0, v[98:99]
	v_lshl_add_u64 v[98:99], s[70:71], 2, v[98:99]
	s_lshl_b32 s16, s86, 2
	v_lshl_add_u64 v[98:99], v[98:99], 0, s[16:17]
	global_store_dword v[98:99], v102, off
.LBB0_1276:
	s_or_b64 exec, exec, s[0:1]
	v_lshl_add_u64 v[108:109], s[42:43], 0, v[32:33]
	v_add_u32_e32 v32, 0x18000, v158
	v_add_u32_e32 v106, 0x18100, v158
	global_load_dwordx4 v[102:105], v32, s[42:43]
	s_waitcnt lgkmcnt(0)
	global_load_dwordx4 v[98:101], v106, s[42:43]
	v_mov_b32_e32 v123, v33
	s_waitcnt vmcnt(5)
	v_lshlrev_b32_e32 v112, 16, v118
	v_and_b32_e32 v113, 0xffff0000, v118
	v_lshl_add_u64 v[110:111], s[42:43], 0, v[122:123]
	v_lshlrev_b32_e32 v118, 16, v119
	v_and_b32_e32 v119, 0xffff0000, v119
	v_lshlrev_b32_e32 v122, 16, v120
	v_and_b32_e32 v123, 0xffff0000, v120
	v_lshlrev_b32_e32 v120, 16, v121
	v_and_b32_e32 v121, 0xffff0000, v121
	v_pk_add_f32 v[94:95], v[94:95], v[112:113]
	v_pk_add_f32 v[96:97], v[96:97], v[118:119]
	v_pk_add_f32 v[112:113], v[92:93], v[120:121]
	v_pk_add_f32 v[92:93], v[90:91], v[122:123]
	v_cvt_pk_bf16_f32 v90, v94, v95
	v_mul_f32_e32 v95, v95, v95
	v_fmac_f32_e32 v95, v94, v94
	v_mul_f32_e32 v94, v97, v97
	v_fmac_f32_e32 v94, v96, v96
	v_add_f32_e32 v94, v95, v94
	v_mul_f32_e32 v95, v93, v93
	v_fmac_f32_e32 v95, v92, v92
	v_add_f32_e32 v94, v95, v94
	v_mul_f32_e32 v95, v113, v113
	v_fmac_f32_e32 v95, v112, v112
	v_cvt_pk_bf16_f32 v91, v96, v97
	v_add_f32_e32 v107, v95, v94
	s_waitcnt vmcnt(4)
	v_lshlrev_b32_e32 v94, 16, v114
	v_and_b32_e32 v95, 0xffff0000, v114
	v_lshlrev_b32_e32 v96, 16, v115
	v_and_b32_e32 v97, 0xffff0000, v115
	v_lshlrev_b32_e32 v114, 16, v116
	v_and_b32_e32 v115, 0xffff0000, v116
	v_pk_add_f32 v[88:89], v[88:89], v[96:97]
	v_pk_add_f32 v[86:87], v[86:87], v[94:95]
	v_pk_add_f32 v[96:97], v[82:83], v[114:115]
	v_mul_f32_e32 v82, v87, v87
	v_mul_f32_e32 v83, v89, v89
	v_fmac_f32_e32 v82, v86, v86
	v_fmac_f32_e32 v83, v88, v88
	v_lshlrev_b32_e32 v116, 16, v117
	v_and_b32_e32 v117, 0xffff0000, v117
	v_add_f32_e32 v82, v82, v83
	v_mul_f32_e32 v83, v97, v97
	v_pk_add_f32 v[94:95], v[84:85], v[116:117]
	v_fmac_f32_e32 v83, v96, v96
	v_add_f32_e32 v82, v83, v82
	v_mul_f32_e32 v83, v95, v95
	v_fmac_f32_e32 v83, v94, v94
	v_add_f32_e32 v82, v83, v82
	v_add_f32_e32 v82, v107, v82
	v_mov_b32_e32 v83, v82
	s_nop 1
	v_permlane16_swap_b32 v83, v82
	v_cvt_pk_bf16_f32 v92, v92, v93
	v_cvt_pk_bf16_f32 v93, v112, v113
	global_store_dwordx4 v[108:109], v[90:93], off
	v_cvt_pk_bf16_f32 v84, v86, v87
	s_waitcnt lgkmcnt(0)
	v_add_f32_e32 v82, v82, v83
	v_mov_b32_e32 v83, v82
	s_nop 1
	v_permlane32_swap_b32 v83, v82
	v_cvt_pk_bf16_f32 v85, v88, v89
	v_cvt_pk_bf16_f32 v86, v96, v97
	v_cvt_pk_bf16_f32 v87, v94, v95
	global_store_dwordx4 v[110:111], v[84:87], off
	s_and_saveexec_b64 s[0:1], vcc
	s_cbranch_execz .LBB0_1278
	v_add_u32_e32 v84, 32, v150
	v_ashrrev_i32_e32 v85, 31, v84
	s_waitcnt lgkmcnt(0)
	v_add_f32_e32 v86, v82, v83
	v_lshlrev_b64 v[82:83], 6, v[84:85]
	v_lshl_add_u64 v[82:83], s[44:45], 0, v[82:83]
	v_lshl_add_u64 v[82:83], s[70:71], 2, v[82:83]
	s_lshl_b32 s16, s86, 2
	v_lshl_add_u64 v[82:83], v[82:83], 0, s[16:17]
	global_store_dword v[82:83], v86, off
.LBB0_1278:
	s_or_b64 exec, exec, s[0:1]
	v_lshl_add_u64 v[92:93], s[42:43], 0, v[32:33]
	v_add_u32_e32 v32, 0x40000, v158
	v_add_u32_e32 v90, 0x40100, v158
	global_load_dwordx4 v[86:89], v32, s[42:43]
	s_waitcnt lgkmcnt(0)
	global_load_dwordx4 v[82:85], v90, s[42:43]
	v_mov_b32_e32 v107, v33
	s_waitcnt vmcnt(5)
	v_lshlrev_b32_e32 v96, 16, v102
	v_and_b32_e32 v97, 0xffff0000, v102
	v_lshl_add_u64 v[94:95], s[42:43], 0, v[106:107]
	v_lshlrev_b32_e32 v102, 16, v103
	v_and_b32_e32 v103, 0xffff0000, v103
	v_lshlrev_b32_e32 v106, 16, v104
	v_and_b32_e32 v107, 0xffff0000, v104
	v_lshlrev_b32_e32 v104, 16, v105
	v_and_b32_e32 v105, 0xffff0000, v105
	v_pk_add_f32 v[78:79], v[78:79], v[96:97]
	v_pk_add_f32 v[80:81], v[80:81], v[102:103]
	v_pk_add_f32 v[96:97], v[76:77], v[104:105]
	v_pk_add_f32 v[76:77], v[74:75], v[106:107]
	v_cvt_pk_bf16_f32 v74, v78, v79
	v_mul_f32_e32 v79, v79, v79
	v_fmac_f32_e32 v79, v78, v78
	v_mul_f32_e32 v78, v81, v81
	v_fmac_f32_e32 v78, v80, v80
	v_add_f32_e32 v78, v79, v78
	v_mul_f32_e32 v79, v77, v77
	v_fmac_f32_e32 v79, v76, v76
	v_add_f32_e32 v78, v79, v78
	v_mul_f32_e32 v79, v97, v97
	v_fmac_f32_e32 v79, v96, v96
	v_cvt_pk_bf16_f32 v75, v80, v81
	v_add_f32_e32 v91, v79, v78
	s_waitcnt vmcnt(4)
	v_lshlrev_b32_e32 v78, 16, v98
	v_and_b32_e32 v79, 0xffff0000, v98
	v_lshlrev_b32_e32 v80, 16, v99
	v_and_b32_e32 v81, 0xffff0000, v99
	v_lshlrev_b32_e32 v98, 16, v100
	v_and_b32_e32 v99, 0xffff0000, v100
	v_pk_add_f32 v[72:73], v[72:73], v[80:81]
	v_pk_add_f32 v[70:71], v[70:71], v[78:79]
	v_pk_add_f32 v[80:81], v[66:67], v[98:99]
	v_mul_f32_e32 v66, v71, v71
	v_mul_f32_e32 v67, v73, v73
	v_fmac_f32_e32 v66, v70, v70
	v_fmac_f32_e32 v67, v72, v72
	v_lshlrev_b32_e32 v100, 16, v101
	v_and_b32_e32 v101, 0xffff0000, v101
	v_add_f32_e32 v66, v66, v67
	v_mul_f32_e32 v67, v81, v81
	v_pk_add_f32 v[78:79], v[68:69], v[100:101]
	v_fmac_f32_e32 v67, v80, v80
	v_add_f32_e32 v66, v67, v66
	v_mul_f32_e32 v67, v79, v79
	v_fmac_f32_e32 v67, v78, v78
	v_add_f32_e32 v66, v67, v66
	v_add_f32_e32 v66, v91, v66
	v_mov_b32_e32 v67, v66
	s_nop 1
	v_permlane16_swap_b32 v67, v66
	v_cvt_pk_bf16_f32 v76, v76, v77
	v_cvt_pk_bf16_f32 v77, v96, v97
	global_store_dwordx4 v[92:93], v[74:77], off
	v_cvt_pk_bf16_f32 v68, v70, v71
	s_waitcnt lgkmcnt(0)
	v_add_f32_e32 v66, v66, v67
	v_mov_b32_e32 v67, v66
	s_nop 1
	v_permlane32_swap_b32 v67, v66
	v_cvt_pk_bf16_f32 v69, v72, v73
	v_cvt_pk_bf16_f32 v70, v80, v81
	v_cvt_pk_bf16_f32 v71, v78, v79
	global_store_dwordx4 v[94:95], v[68:71], off
	s_and_saveexec_b64 s[0:1], vcc
	s_cbranch_execz .LBB0_1280
	v_add_u32_e32 v68, 48, v150
	v_ashrrev_i32_e32 v69, 31, v68
	s_waitcnt lgkmcnt(0)
	v_add_f32_e32 v70, v66, v67
	v_lshlrev_b64 v[66:67], 6, v[68:69]
	v_lshl_add_u64 v[66:67], s[44:45], 0, v[66:67]
	v_lshl_add_u64 v[66:67], s[70:71], 2, v[66:67]
	s_lshl_b32 s16, s86, 2
	v_lshl_add_u64 v[66:67], v[66:67], 0, s[16:17]
	global_store_dword v[66:67], v70, off
.LBB0_1280:
	s_or_b64 exec, exec, s[0:1]
	v_lshl_add_u64 v[76:77], s[42:43], 0, v[32:33]
	v_add_u32_e32 v32, 0x48000, v158
	v_add_u32_e32 v74, 0x48100, v158
	global_load_dwordx4 v[70:73], v32, s[42:43]
	s_waitcnt lgkmcnt(0)
	global_load_dwordx4 v[66:69], v74, s[42:43]
	v_mov_b32_e32 v91, v33
	s_waitcnt vmcnt(5)
	v_lshlrev_b32_e32 v80, 16, v86
	v_and_b32_e32 v81, 0xffff0000, v86
	v_lshl_add_u64 v[78:79], s[42:43], 0, v[90:91]
	v_lshlrev_b32_e32 v86, 16, v87
	v_and_b32_e32 v87, 0xffff0000, v87
	v_lshlrev_b32_e32 v90, 16, v88
	v_and_b32_e32 v91, 0xffff0000, v88
	v_lshlrev_b32_e32 v88, 16, v89
	v_and_b32_e32 v89, 0xffff0000, v89
	v_pk_add_f32 v[62:63], v[62:63], v[80:81]
	v_pk_add_f32 v[64:65], v[64:65], v[86:87]
	v_pk_add_f32 v[80:81], v[60:61], v[88:89]
	v_pk_add_f32 v[60:61], v[58:59], v[90:91]
	v_cvt_pk_bf16_f32 v58, v62, v63
	v_mul_f32_e32 v63, v63, v63
	v_fmac_f32_e32 v63, v62, v62
	v_mul_f32_e32 v62, v65, v65
	v_fmac_f32_e32 v62, v64, v64
	v_add_f32_e32 v62, v63, v62
	v_mul_f32_e32 v63, v61, v61
	v_fmac_f32_e32 v63, v60, v60
	v_add_f32_e32 v62, v63, v62
	v_mul_f32_e32 v63, v81, v81
	v_fmac_f32_e32 v63, v80, v80
	v_cvt_pk_bf16_f32 v59, v64, v65
	v_add_f32_e32 v75, v63, v62
	s_waitcnt vmcnt(4)
	v_lshlrev_b32_e32 v62, 16, v82
	v_and_b32_e32 v63, 0xffff0000, v82
	v_lshlrev_b32_e32 v64, 16, v83
	v_and_b32_e32 v65, 0xffff0000, v83
	v_lshlrev_b32_e32 v82, 16, v84
	v_and_b32_e32 v83, 0xffff0000, v84
	v_pk_add_f32 v[56:57], v[56:57], v[64:65]
	v_pk_add_f32 v[54:55], v[54:55], v[62:63]
	v_pk_add_f32 v[64:65], v[50:51], v[82:83]
	v_mul_f32_e32 v50, v55, v55
	v_mul_f32_e32 v51, v57, v57
	v_fmac_f32_e32 v50, v54, v54
	v_fmac_f32_e32 v51, v56, v56
	v_lshlrev_b32_e32 v84, 16, v85
	v_and_b32_e32 v85, 0xffff0000, v85
	v_add_f32_e32 v50, v50, v51
	v_mul_f32_e32 v51, v65, v65
	v_pk_add_f32 v[62:63], v[52:53], v[84:85]
	v_fmac_f32_e32 v51, v64, v64
	v_add_f32_e32 v50, v51, v50
	v_mul_f32_e32 v51, v63, v63
	v_fmac_f32_e32 v51, v62, v62
	v_add_f32_e32 v50, v51, v50
	v_add_f32_e32 v50, v75, v50
	v_mov_b32_e32 v51, v50
	s_nop 1
	v_permlane16_swap_b32 v51, v50
	v_cvt_pk_bf16_f32 v60, v60, v61
	v_cvt_pk_bf16_f32 v61, v80, v81
	global_store_dwordx4 v[76:77], v[58:61], off
	v_cvt_pk_bf16_f32 v52, v54, v55
	s_waitcnt lgkmcnt(0)
	v_add_f32_e32 v50, v50, v51
	v_mov_b32_e32 v51, v50
	s_nop 1
	v_permlane32_swap_b32 v51, v50
	v_cvt_pk_bf16_f32 v53, v56, v57
	v_cvt_pk_bf16_f32 v54, v64, v65
	v_cvt_pk_bf16_f32 v55, v62, v63
	global_store_dwordx4 v[78:79], v[52:55], off
	s_and_saveexec_b64 s[0:1], vcc
	s_cbranch_execz .LBB0_1282
	v_add_u32_e32 v52, 0x80, v150
	v_ashrrev_i32_e32 v53, 31, v52
	s_waitcnt lgkmcnt(0)
	v_add_f32_e32 v54, v50, v51
	v_lshlrev_b64 v[50:51], 6, v[52:53]
	v_lshl_add_u64 v[50:51], s[44:45], 0, v[50:51]
	v_lshl_add_u64 v[50:51], s[70:71], 2, v[50:51]
	s_lshl_b32 s16, s86, 2
	v_lshl_add_u64 v[50:51], v[50:51], 0, s[16:17]
	global_store_dword v[50:51], v54, off
.LBB0_1282:
	s_or_b64 exec, exec, s[0:1]
	v_lshl_add_u64 v[60:61], s[42:43], 0, v[32:33]
	v_add_u32_e32 v32, 0x50000, v158
	v_add_u32_e32 v58, 0x50100, v158
	global_load_dwordx4 v[54:57], v32, s[42:43]
	s_waitcnt lgkmcnt(0)
	global_load_dwordx4 v[50:53], v58, s[42:43]
	v_mov_b32_e32 v75, v33
	s_waitcnt vmcnt(5)
	v_lshlrev_b32_e32 v64, 16, v70
	v_and_b32_e32 v65, 0xffff0000, v70
	v_lshl_add_u64 v[62:63], s[42:43], 0, v[74:75]
	v_lshlrev_b32_e32 v70, 16, v71
	v_and_b32_e32 v71, 0xffff0000, v71
	v_lshlrev_b32_e32 v74, 16, v72
	v_and_b32_e32 v75, 0xffff0000, v72
	v_lshlrev_b32_e32 v72, 16, v73
	v_and_b32_e32 v73, 0xffff0000, v73
	v_pk_add_f32 v[46:47], v[46:47], v[64:65]
	v_pk_add_f32 v[48:49], v[48:49], v[70:71]
	v_pk_add_f32 v[64:65], v[44:45], v[72:73]
	v_pk_add_f32 v[44:45], v[42:43], v[74:75]
	v_cvt_pk_bf16_f32 v42, v46, v47
	v_mul_f32_e32 v47, v47, v47
	v_fmac_f32_e32 v47, v46, v46
	v_mul_f32_e32 v46, v49, v49
	v_fmac_f32_e32 v46, v48, v48
	v_add_f32_e32 v46, v47, v46
	v_mul_f32_e32 v47, v45, v45
	v_fmac_f32_e32 v47, v44, v44
	v_add_f32_e32 v46, v47, v46
	v_mul_f32_e32 v47, v65, v65
	v_fmac_f32_e32 v47, v64, v64
	v_cvt_pk_bf16_f32 v43, v48, v49
	v_add_f32_e32 v59, v47, v46
	s_waitcnt vmcnt(4)
	v_lshlrev_b32_e32 v46, 16, v66
	v_and_b32_e32 v47, 0xffff0000, v66
	v_lshlrev_b32_e32 v48, 16, v67
	v_and_b32_e32 v49, 0xffff0000, v67
	v_lshlrev_b32_e32 v66, 16, v68
	v_and_b32_e32 v67, 0xffff0000, v68
	v_pk_add_f32 v[40:41], v[40:41], v[48:49]
	v_pk_add_f32 v[38:39], v[38:39], v[46:47]
	v_pk_add_f32 v[48:49], v[34:35], v[66:67]
	v_mul_f32_e32 v34, v39, v39
	v_mul_f32_e32 v35, v41, v41
	v_fmac_f32_e32 v34, v38, v38
	v_fmac_f32_e32 v35, v40, v40
	v_lshlrev_b32_e32 v68, 16, v69
	v_and_b32_e32 v69, 0xffff0000, v69
	v_add_f32_e32 v34, v34, v35
	v_mul_f32_e32 v35, v49, v49
	v_pk_add_f32 v[46:47], v[36:37], v[68:69]
	v_fmac_f32_e32 v35, v48, v48
	v_add_f32_e32 v34, v35, v34
	v_mul_f32_e32 v35, v47, v47
	v_fmac_f32_e32 v35, v46, v46
	v_add_f32_e32 v34, v35, v34
	v_add_f32_e32 v34, v59, v34
	v_mov_b32_e32 v35, v34
	s_nop 1
	v_permlane16_swap_b32 v35, v34
	v_cvt_pk_bf16_f32 v44, v44, v45
	v_cvt_pk_bf16_f32 v45, v64, v65
	global_store_dwordx4 v[60:61], v[42:45], off
	v_cvt_pk_bf16_f32 v36, v38, v39
	s_waitcnt lgkmcnt(0)
	v_add_f32_e32 v34, v34, v35
	v_mov_b32_e32 v35, v34
	s_nop 1
	v_permlane32_swap_b32 v35, v34
	v_cvt_pk_bf16_f32 v37, v40, v41
	v_cvt_pk_bf16_f32 v38, v48, v49
	v_cvt_pk_bf16_f32 v39, v46, v47
	global_store_dwordx4 v[62:63], v[36:39], off
	s_and_saveexec_b64 s[0:1], vcc
	s_cbranch_execz .LBB0_1284
	v_add_u32_e32 v36, 0x90, v150
	v_ashrrev_i32_e32 v37, 31, v36
	s_waitcnt lgkmcnt(0)
	v_add_f32_e32 v38, v34, v35
	v_lshlrev_b64 v[34:35], 6, v[36:37]
	v_lshl_add_u64 v[34:35], s[44:45], 0, v[34:35]
	v_lshl_add_u64 v[34:35], s[70:71], 2, v[34:35]
	s_lshl_b32 s16, s86, 2
	v_lshl_add_u64 v[34:35], v[34:35], 0, s[16:17]
	global_store_dword v[34:35], v38, off
.LBB0_1284:
	s_or_b64 exec, exec, s[0:1]
	v_lshl_add_u64 v[44:45], s[42:43], 0, v[32:33]
	v_add_u32_e32 v32, 0x58000, v158
	v_add_u32_e32 v42, 0x58100, v158
	global_load_dwordx4 v[38:41], v32, s[42:43]
	s_waitcnt lgkmcnt(0)
	global_load_dwordx4 v[34:37], v42, s[42:43]
	v_mov_b32_e32 v59, v33
	s_waitcnt vmcnt(5)
	v_lshlrev_b32_e32 v48, 16, v54
	v_and_b32_e32 v49, 0xffff0000, v54
	v_lshl_add_u64 v[46:47], s[42:43], 0, v[58:59]
	v_lshlrev_b32_e32 v54, 16, v55
	v_and_b32_e32 v55, 0xffff0000, v55
	v_lshlrev_b32_e32 v58, 16, v56
	v_and_b32_e32 v59, 0xffff0000, v56
	v_lshlrev_b32_e32 v56, 16, v57
	v_and_b32_e32 v57, 0xffff0000, v57
	v_pk_add_f32 v[28:29], v[28:29], v[48:49]
	v_pk_add_f32 v[30:31], v[30:31], v[54:55]
	v_pk_add_f32 v[48:49], v[26:27], v[56:57]
	v_pk_add_f32 v[26:27], v[24:25], v[58:59]
	v_cvt_pk_bf16_f32 v24, v28, v29
	v_mul_f32_e32 v29, v29, v29
	v_fmac_f32_e32 v29, v28, v28
	v_mul_f32_e32 v28, v31, v31
	v_fmac_f32_e32 v28, v30, v30
	v_add_f32_e32 v28, v29, v28
	v_mul_f32_e32 v29, v27, v27
	v_fmac_f32_e32 v29, v26, v26
	v_add_f32_e32 v28, v29, v28
	v_mul_f32_e32 v29, v49, v49
	v_fmac_f32_e32 v29, v48, v48
	v_cvt_pk_bf16_f32 v25, v30, v31
	v_add_f32_e32 v43, v29, v28
	s_waitcnt vmcnt(4)
	v_lshlrev_b32_e32 v28, 16, v50
	v_and_b32_e32 v29, 0xffff0000, v50
	v_lshlrev_b32_e32 v30, 16, v51
	v_and_b32_e32 v31, 0xffff0000, v51
	v_lshlrev_b32_e32 v50, 16, v52
	v_and_b32_e32 v51, 0xffff0000, v52
	v_pk_add_f32 v[22:23], v[22:23], v[30:31]
	v_pk_add_f32 v[20:21], v[20:21], v[28:29]
	v_pk_add_f32 v[30:31], v[16:17], v[50:51]
	v_mul_f32_e32 v16, v21, v21
	v_mul_f32_e32 v17, v23, v23
	v_fmac_f32_e32 v16, v20, v20
	v_fmac_f32_e32 v17, v22, v22
	v_lshlrev_b32_e32 v52, 16, v53
	v_and_b32_e32 v53, 0xffff0000, v53
	v_add_f32_e32 v16, v16, v17
	v_mul_f32_e32 v17, v31, v31
	v_pk_add_f32 v[28:29], v[18:19], v[52:53]
	v_fmac_f32_e32 v17, v30, v30
	v_add_f32_e32 v16, v17, v16
	v_mul_f32_e32 v17, v29, v29
	v_fmac_f32_e32 v17, v28, v28
	v_add_f32_e32 v16, v17, v16
	v_add_f32_e32 v16, v43, v16
	v_mov_b32_e32 v17, v16
	s_nop 1
	v_permlane16_swap_b32 v17, v16
	v_cvt_pk_bf16_f32 v26, v26, v27
	v_cvt_pk_bf16_f32 v27, v48, v49
	global_store_dwordx4 v[44:45], v[24:27], off
	v_cvt_pk_bf16_f32 v18, v20, v21
	s_waitcnt lgkmcnt(0)
	v_add_f32_e32 v16, v16, v17
	v_mov_b32_e32 v17, v16
	s_nop 1
	v_permlane32_swap_b32 v17, v16
	v_cvt_pk_bf16_f32 v19, v22, v23
	v_cvt_pk_bf16_f32 v20, v30, v31
	v_cvt_pk_bf16_f32 v21, v28, v29
	global_store_dwordx4 v[46:47], v[18:21], off
	s_and_saveexec_b64 s[0:1], vcc
	s_cbranch_execz .LBB0_1286
	v_add_u32_e32 v18, 0xa0, v150
	v_ashrrev_i32_e32 v19, 31, v18
	s_waitcnt lgkmcnt(0)
	v_add_f32_e32 v20, v16, v17
	v_lshlrev_b64 v[16:17], 6, v[18:19]
	v_lshl_add_u64 v[16:17], s[44:45], 0, v[16:17]
	v_lshl_add_u64 v[16:17], s[70:71], 2, v[16:17]
	s_lshl_b32 s16, s86, 2
	v_lshl_add_u64 v[16:17], v[16:17], 0, s[16:17]
	global_store_dword v[16:17], v20, off
.LBB0_1286:
	s_or_b64 exec, exec, s[0:1]
	s_waitcnt vmcnt(3)
	v_lshlrev_b32_e32 v20, 16, v38
	v_and_b32_e32 v21, 0xffff0000, v38
	v_lshlrev_b32_e32 v22, 16, v39
	v_and_b32_e32 v23, 0xffff0000, v39
	v_lshlrev_b32_e32 v24, 16, v40
	v_and_b32_e32 v25, 0xffff0000, v40
	v_lshlrev_b32_e32 v26, 16, v41
	v_and_b32_e32 v27, 0xffff0000, v41
	v_pk_add_f32 v[12:13], v[12:13], v[20:21]
	v_pk_add_f32 v[14:15], v[14:15], v[22:23]
	v_pk_add_f32 v[20:21], v[10:11], v[26:27]
	v_pk_add_f32 v[10:11], v[8:9], v[24:25]
	v_cvt_pk_bf16_f32 v8, v12, v13
	v_mul_f32_e32 v13, v13, v13
	v_fmac_f32_e32 v13, v12, v12
	v_mul_f32_e32 v12, v15, v15
	v_fmac_f32_e32 v12, v14, v14
	v_add_f32_e32 v12, v13, v12
	v_mul_f32_e32 v13, v11, v11
	v_fmac_f32_e32 v13, v10, v10
	v_add_f32_e32 v12, v13, v12
	v_mul_f32_e32 v13, v21, v21
	v_fmac_f32_e32 v13, v20, v20
	v_cvt_pk_bf16_f32 v9, v14, v15
	v_add_f32_e32 v26, v13, v12
	s_waitcnt vmcnt(2)
	v_lshlrev_b32_e32 v12, 16, v34
	v_and_b32_e32 v13, 0xffff0000, v34
	v_lshlrev_b32_e32 v14, 16, v35
	v_and_b32_e32 v15, 0xffff0000, v35
	v_lshlrev_b32_e32 v22, 16, v36
	v_and_b32_e32 v23, 0xffff0000, v36
	v_pk_add_f32 v[6:7], v[6:7], v[14:15]
	v_pk_add_f32 v[4:5], v[4:5], v[12:13]
	v_pk_add_f32 v[14:15], v[0:1], v[22:23]
	v_mul_f32_e32 v0, v5, v5
	v_mul_f32_e32 v1, v7, v7
	v_fmac_f32_e32 v0, v4, v4
	v_fmac_f32_e32 v1, v6, v6
	v_lshlrev_b32_e32 v24, 16, v37
	v_and_b32_e32 v25, 0xffff0000, v37
	v_add_f32_e32 v0, v0, v1
	v_mul_f32_e32 v1, v15, v15
	v_pk_add_f32 v[12:13], v[2:3], v[24:25]
	v_fmac_f32_e32 v1, v14, v14
	v_add_f32_e32 v0, v1, v0
	v_mul_f32_e32 v1, v13, v13
	v_fmac_f32_e32 v1, v12, v12
	v_add_f32_e32 v0, v1, v0
	v_add_f32_e32 v0, v26, v0
	v_mov_b32_e32 v1, v0
	s_nop 1
	v_permlane16_swap_b32 v1, v0
	v_mov_b32_e32 v43, v33
	s_waitcnt lgkmcnt(1)
	v_lshl_add_u64 v[16:17], s[42:43], 0, v[32:33]
	v_lshl_add_u64 v[18:19], s[42:43], 0, v[42:43]
	v_cvt_pk_bf16_f32 v10, v10, v11
	s_waitcnt lgkmcnt(0)
	v_add_f32_e32 v0, v0, v1
	v_mov_b32_e32 v1, v0
	s_nop 1
	v_permlane32_swap_b32 v1, v0
	v_cvt_pk_bf16_f32 v11, v20, v21
	global_store_dwordx4 v[16:17], v[8:11], off
	v_cvt_pk_bf16_f32 v2, v4, v5
	v_cvt_pk_bf16_f32 v3, v6, v7
	v_cvt_pk_bf16_f32 v4, v14, v15
	v_cvt_pk_bf16_f32 v5, v12, v13
	global_store_dwordx4 v[18:19], v[2:5], off
	s_and_saveexec_b64 s[0:1], vcc
	s_cbranch_execz .LBB0_1288
	v_add_u32_e32 v2, 0xb0, v150
	v_ashrrev_i32_e32 v3, 31, v2
	s_waitcnt lgkmcnt(0)
	v_add_f32_e32 v4, v0, v1
	v_lshlrev_b64 v[0:1], 6, v[2:3]
	v_lshl_add_u64 v[0:1], s[44:45], 0, v[0:1]
	v_lshl_add_u64 v[0:1], s[70:71], 2, v[0:1]
	s_lshl_b32 s16, s86, 2
	v_lshl_add_u64 v[0:1], v[0:1], 0, s[16:17]
	global_store_dword v[0:1], v4, off
